# attention: V-tile DMA issue moved behind the four opening K-fragment ds_reads of each QK section; leading vmcnt(0) dropped
# baseline (speedup 1.0000x reference)
; __device__ __forceinline__ void finishSM(f32x16& p0, f32x16& p1, float alpha, float& l_reg, bf16x8& pa0, bf16x8& pa1, bf16x8& pa2, bf16x8& pa3) {
;     for (int r = 0; r < 16; ++r) p1[r] = __builtin_amdgcn_exp2f(p1[r]);
;     float ps = 0; for (int r = 0; r < 16; ++r) ps += p0[r]; for (int r = 0; r < 16; ++r) ps += p1[r];
;     { auto rr = __builtin_amdgcn_permlane32_swap(__float_as_uint(ps), __float_as_uint(ps), false, false);
;       ps = __uint_as_float(rr[0]) + __uint_as_float(rr[1]); }
;     l_reg = l_reg * alpha + ps;
;     ...
;     PK4(p0, 0, pa0); PK4(p0, 8, pa1); PK4(p1, 0, pa2); PK4(p1, 8, pa3);
;     ...
; }
; template <int KB>
; __device__ __forceinline__ void qkt(f32x16& p0, f32x16& p1, const char* K_lds, int r32, int hi, const bf16x8* qr) {
;     p0 = f32x16{}; p1 = f32x16{};
;     const char* kb[4];
; #pragma unroll
;     for (int dd = 0; dd < 4; ++dd) kb[dd] = K_lds + KB * SHM_K + KSWZ(r32, (dd * 16 + hi * 8) * 2);
; #pragma unroll
;     for (int d0 = 0; d0 < 8; ++d0) { const char* a = kb[d0 & 3] + (d0 >> 2) * 128;
;         bf16x8 b0 = *reinterpret_cast<const bf16x8*>(a);
;         bf16x8 b1 = *reinterpret_cast<const bf16x8*>(a + 32 * 256);
;         p0 = __builtin_amdgcn_mfma_f32_32x32x16_bf16(b0, qr[d0], p0, 0, 0, 0);
;         p1 = __builtin_amdgcn_mfma_f32_32x32x16_bf16(b1, qr[d0], p1, 0, 0, 0); }
; }
.LBB0_89:
	ds_read_b128 v[66:69], v169 offset:49152
	ds_read_b128 v[70:73], v169 offset:57344
	ds_read_b128 v[100:103], v193 offset:49152
	ds_read_b128 v[136:139], v193 offset:57344
	s_cmp_eq_u32 s100, 0
	s_cbranch_scc1 .Lmy_hs1_nov
	s_lshl_b32 m0, s32, 1
	s_sub_i32 m0, m0, 0xc000
	s_nop 0
	global_load_lds_dwordx4 v[242:243], off
	s_add_i32 m0, m0, 896
	s_nop 0
	global_load_lds_dwordx4 v[242:243], off offset:128
.Lmy_hs1_nov:
	s_mov_b32 s100, 0
	v_add_f32_e32 v148, 0, v231
	v_add_f32_e32 v148, v233, v148
	v_add_f32_e32 v148, v229, v148
	v_add_f32_e32 v148, v232, v148
	v_add_f32_e32 v148, v228, v148
	v_add_f32_e32 v148, v230, v148
	v_add_f32_e32 v148, v226, v148
	v_add_f32_e32 v148, v227, v148
	v_add_f32_e32 v148, v223, v148
	v_add_f32_e32 v148, v225, v148
	v_add_f32_e32 v148, v209, v148
	v_add_f32_e32 v148, v224, v148
	v_add_f32_e32 v148, v206, v148
	v_add_f32_e32 v148, v208, v148
	v_add_f32_e32 v148, v205, v148
	v_add_f32_e32 v148, v207, v148
	v_exp_f32_e32 v140, v152
	v_exp_f32_e32 v141, v153
	v_exp_f32_e32 v142, v180
	v_exp_f32_e32 v143, v181
	s_waitcnt lgkmcnt(3)
	v_mfma_f32_32x32x16_bf16 v[82:97], v[66:69], v[132:135], 0
	v_exp_f32_e32 v144, v160
	v_exp_f32_e32 v145, v161
	v_exp_f32_e32 v146, v154
	v_exp_f32_e32 v147, v155
	s_waitcnt lgkmcnt(2)
	v_mfma_f32_32x32x16_bf16 v[66:81], v[70:73], v[132:135], 0
	v_exp_f32_e32 v178, v178
	v_exp_f32_e32 v179, v179
	v_exp_f32_e32 v162, v162
	v_exp_f32_e32 v163, v163
	s_waitcnt lgkmcnt(1)
	v_mfma_f32_32x32x16_bf16 v[82:97], v[100:103], v[128:131], v[82:97]
	v_add_f32_e32 v148, v178, v148
	v_add_f32_e32 v148, v179, v148
	v_add_f32_e32 v148, v162, v148
	v_exp_f32_e32 v158, v158
	s_waitcnt lgkmcnt(0)
	v_mfma_f32_32x32x16_bf16 v[66:81], v[136:139], v[128:131], v[66:81]
	v_exp_f32_e32 v159, v159
	v_exp_f32_e32 v156, v156
	v_exp_f32_e32 v157, v157
	v_add_f32_e32 v148, v163, v148
	ds_read_b128 v[100:103], v194 offset:49152
	ds_read_b128 v[136:139], v194 offset:57344
	s_waitcnt lgkmcnt(1)
	v_mfma_f32_32x32x16_bf16 v[82:97], v[100:103], v[124:127], v[82:97]
	v_add_f32_e32 v148, v158, v148
	v_add_f32_e32 v148, v159, v148
	v_add_f32_e32 v148, v156, v148
	v_add_f32_e32 v148, v157, v148
	s_waitcnt lgkmcnt(0)
	v_mfma_f32_32x32x16_bf16 v[66:81], v[136:139], v[124:127], v[66:81]
	v_add_f32_e32 v148, v140, v148
	v_add_f32_e32 v148, v141, v148
	v_add_f32_e32 v148, v142, v148
	v_add_f32_e32 v148, v143, v148
	ds_read_b128 v[100:103], v195 offset:49152
	ds_read_b128 v[136:139], v195 offset:57344
	s_waitcnt lgkmcnt(1)
	v_mfma_f32_32x32x16_bf16 v[82:97], v[100:103], v[120:123], v[82:97]
	v_add_f32_e32 v148, v144, v148
	v_add_f32_e32 v148, v145, v148
	v_add_f32_e32 v148, v146, v148
	v_add_f32_e32 v199, v147, v148
	s_waitcnt lgkmcnt(0)
	v_mfma_f32_32x32x16_bf16 v[66:81], v[136:139], v[120:123], v[66:81]
	v_mov_b32_e32 v200, v199
	s_nop 1
	v_permlane32_swap_b32_e32 v199, v200
	v_cvt_pk_bf16_f32 v148, v231, v233
	v_cvt_pk_bf16_f32 v149, v229, v232
	v_cvt_pk_bf16_f32 v150, v228, v230
	ds_read_b128 v[100:103], v169 offset:49280
	ds_read_b128 v[136:139], v169 offset:57472
	s_waitcnt lgkmcnt(1)
	v_mfma_f32_32x32x16_bf16 v[82:97], v[100:103], v[116:119], v[82:97]
	v_cvt_pk_bf16_f32 v151, v226, v227
	v_cvt_pk_bf16_f32 v152, v223, v225
	v_cvt_pk_bf16_f32 v153, v209, v224
	s_waitcnt lgkmcnt(0)
	v_mfma_f32_32x32x16_bf16 v[66:81], v[136:139], v[116:119], v[66:81]
	v_cvt_pk_bf16_f32 v154, v206, v208
	v_cvt_pk_bf16_f32 v155, v205, v207
	v_cvt_pk_bf16_f32 v158, v158, v159
	ds_read_b128 v[100:103], v193 offset:49280
	ds_read_b128 v[136:139], v193 offset:57472
	s_waitcnt lgkmcnt(1)
	v_mfma_f32_32x32x16_bf16 v[82:97], v[100:103], v[112:115], v[82:97]
	v_cvt_pk_bf16_f32 v159, v156, v157
	v_cvt_pk_bf16_f32 v156, v178, v179
	v_cvt_pk_bf16_f32 v157, v162, v163
	s_waitcnt lgkmcnt(0)
	v_mfma_f32_32x32x16_bf16 v[66:81], v[136:139], v[112:115], v[66:81]
	v_cvt_pk_bf16_f32 v160, v140, v141
	v_cvt_pk_bf16_f32 v161, v142, v143
	v_cvt_pk_bf16_f32 v162, v144, v145
	ds_read_b128 v[100:103], v194 offset:49280
	ds_read_b128 v[136:139], v194 offset:57472
	s_waitcnt lgkmcnt(1)
	v_mfma_f32_32x32x16_bf16 v[82:97], v[100:103], v[108:111], v[82:97]
	v_cvt_pk_bf16_f32 v163, v146, v147
	s_nop 0
	v_permlane32_swap_b32_e32 v148, v150
	v_permlane32_swap_b32_e32 v149, v151
	s_waitcnt lgkmcnt(0)
	v_mfma_f32_32x32x16_bf16 v[66:81], v[136:139], v[108:111], v[66:81]
	v_permlane32_swap_b32_e32 v152, v154
	v_permlane32_swap_b32_e32 v153, v155
	v_permlane32_swap_b32_e32 v156, v158
	ds_read_b128 v[100:103], v195 offset:49280
	ds_read_b128 v[136:139], v195 offset:57472
	ds_read_b64_tr_b16 v[172:173], v185 offset:0
	ds_read_b64_tr_b16 v[174:175], v185 offset:0x800
	ds_read_b64_tr_b16 v[202:203], v185 offset:0x1000
	ds_read_b64_tr_b16 v[204:205], v185 offset:0x1800
	ds_read_b64_tr_b16 v[206:207], v185 offset:0x2000
	ds_read_b64_tr_b16 v[208:209], v185 offset:0x2800
	ds_read_b64_tr_b16 v[224:225], v185 offset:0x3000
	ds_read_b64_tr_b16 v[226:227], v185 offset:0x3800
	s_waitcnt lgkmcnt(9)
	v_mfma_f32_32x32x16_bf16 v[82:97], v[100:103], v[104:107], v[82:97]
	v_permlane32_swap_b32_e32 v157, v159
	v_permlane32_swap_b32_e32 v160, v162
	v_permlane32_swap_b32_e32 v161, v163
	s_waitcnt lgkmcnt(8)
	v_mfma_f32_32x32x16_bf16 v[66:81], v[136:139], v[104:107], v[66:81]
	v_add_u32_e32 v178, s7, v166
	v_add_u32_e32 v100, 1, v178
	v_add_u32_e32 v102, 33, v178
	v_ashrrev_i32_e32 v101, 31, v100
	v_ashrrev_i32_e32 v103, 31, v102
	v_lshlrev_b64 v[140:141], 8, v[100:101]
	v_lshlrev_b64 v[142:143], 8, v[102:103]
	v_lshl_add_u64 v[100:101], v[238:239], 0, v[140:141]
	v_lshl_add_u64 v[140:141], v[234:235], 0, v[140:141]
	v_lshl_add_u64 v[144:145], v[234:235], 0, v[142:143]
	s_nop 0
	s_nop 0
	s_mov_b32 m0, s32
	s_nop 0
	global_load_lds_dwordx4 v[140:141], off
	s_nop 0
	s_add_i32 m0, s32, 0x2000
	s_nop 0
	global_load_lds_dwordx4 v[144:145], off
	s_waitcnt lgkmcnt(0)
; __device__ __forceinline__ void mask_tile(f32x16& p0, f32x16& p1, int dq, unsigned W) {
;     const float NEG = -__builtin_inff();
; #pragma unroll
;     for (int r = 0; r < 16; ++r) {
;         const int c = (r & 3) + 8 * (r >> 2);
;         if ((unsigned)(dq - c) >= W) p0[r] = NEG;
;         if ((unsigned)(dq - c - 32) >= W) p1[r] = NEG;
;     }
; }
; template <int VB>
; __device__ __forceinline__ void pv_tile(f32x16* o, int vb0, bf16x8 pa0, bf16x8 pa1, bf16x8 pa2, bf16x8 pa3) {
;     ...
;     PV_D0(0); PV_D0(1); PV_D0(2); PV_D0(3);
	s_nop 0
	v_mfma_f32_32x32x16_bf16 v[50:65], v[148:151], v[172:175], v[50:65]
	ds_read_b64_tr_b16 v[172:173], v185 offset:0x200
	ds_read_b64_tr_b16 v[174:175], v185 offset:0xa00
	v_mfma_f32_32x32x16_bf16 v[50:65], v[152:155], v[202:205], v[50:65]
	ds_read_b64_tr_b16 v[202:203], v185 offset:0x1200
	ds_read_b64_tr_b16 v[204:205], v185 offset:0x1a00
	v_mfma_f32_32x32x16_bf16 v[50:65], v[156:159], v[206:209], v[50:65]
	ds_read_b64_tr_b16 v[206:207], v185 offset:0x2200
	ds_read_b64_tr_b16 v[208:209], v185 offset:0x2a00
	v_mfma_f32_32x32x16_bf16 v[50:65], v[160:163], v[224:227], v[50:65]
	ds_read_b64_tr_b16 v[224:225], v185 offset:0x3200
	ds_read_b64_tr_b16 v[226:227], v185 offset:0x3a00
	s_waitcnt lgkmcnt(0)
	v_mfma_f32_32x32x16_bf16 v[34:49], v[148:151], v[172:175], v[34:49]
	ds_read_b64_tr_b16 v[172:173], v185 offset:0x400
	ds_read_b64_tr_b16 v[174:175], v185 offset:0xc00
	v_mfma_f32_32x32x16_bf16 v[34:49], v[152:155], v[202:205], v[34:49]
	ds_read_b64_tr_b16 v[202:203], v185 offset:0x1400
	ds_read_b64_tr_b16 v[204:205], v185 offset:0x1c00
	v_mfma_f32_32x32x16_bf16 v[34:49], v[156:159], v[206:209], v[34:49]
	ds_read_b64_tr_b16 v[206:207], v185 offset:0x2400
	ds_read_b64_tr_b16 v[208:209], v185 offset:0x2c00
	v_mfma_f32_32x32x16_bf16 v[34:49], v[160:163], v[224:227], v[34:49]
	ds_read_b64_tr_b16 v[224:225], v185 offset:0x3400
	ds_read_b64_tr_b16 v[226:227], v185 offset:0x3c00
	s_waitcnt lgkmcnt(0)
	v_mfma_f32_32x32x16_bf16 v[18:33], v[148:151], v[172:175], v[18:33]
	ds_read_b64_tr_b16 v[172:173], v185 offset:0x600
	ds_read_b64_tr_b16 v[174:175], v185 offset:0xe00
	v_mfma_f32_32x32x16_bf16 v[18:33], v[152:155], v[202:205], v[18:33]
	ds_read_b64_tr_b16 v[202:203], v185 offset:0x1600
	ds_read_b64_tr_b16 v[204:205], v185 offset:0x1e00
	v_mfma_f32_32x32x16_bf16 v[18:33], v[156:159], v[206:209], v[18:33]
	ds_read_b64_tr_b16 v[206:207], v185 offset:0x2600
	ds_read_b64_tr_b16 v[208:209], v185 offset:0x2e00
	v_mfma_f32_32x32x16_bf16 v[18:33], v[160:163], v[224:227], v[18:33]
	ds_read_b64_tr_b16 v[224:225], v185 offset:0x3600
	ds_read_b64_tr_b16 v[226:227], v185 offset:0x3e00
	s_waitcnt lgkmcnt(0)
	v_mfma_f32_32x32x16_bf16 v[2:17], v[148:151], v[172:175], v[2:17]
	s_cmp_le_i32 s7, s6
	v_mfma_f32_32x32x16_bf16 v[2:17], v[152:155], v[202:205], v[2:17]
	v_mfma_f32_32x32x16_bf16 v[2:17], v[156:159], v[206:209], v[2:17]
	v_mfma_f32_32x32x16_bf16 v[2:17], v[160:163], v[224:227], v[2:17]
	s_cbranch_scc1 .LBB0_91
	v_add_u32_e32 v148, 0x4000007b, v197
	v_cmp_gt_u32_e32 vcc, 2.0, v148
	v_add_u32_e32 v148, 0x5b, v197
	s_nop 0
	v_cndmask_b32_e32 v82, v220, v82, vcc
	v_cmp_lt_u32_e32 vcc, s33, v148
	v_add_u32_e32 v148, 0x7a, v197
	s_nop 0
	v_cndmask_b32_e32 v66, v220, v66, vcc
	v_cmp_lt_u32_e32 vcc, s33, v148
	v_add_u32_e32 v148, 0x5a, v197
	s_nop 0
	v_cndmask_b32_e32 v83, v220, v83, vcc
	v_cmp_lt_u32_e32 vcc, s33, v148
	v_add_u32_e32 v148, 0x79, v197
	s_nop 0
	v_cndmask_b32_e32 v67, v220, v67, vcc
	v_cmp_lt_u32_e32 vcc, s33, v148
	v_add_u32_e32 v148, 0x59, v197
	s_nop 0
	v_cndmask_b32_e32 v84, v220, v84, vcc
	v_cmp_lt_u32_e32 vcc, s33, v148
	v_add_u32_e32 v148, 0x78, v197
	s_nop 0
	v_cndmask_b32_e32 v68, v220, v68, vcc
	v_cmp_lt_u32_e32 vcc, s33, v148
	v_add_u32_e32 v148, 0x58, v197
	s_nop 0
	v_cndmask_b32_e32 v85, v220, v85, vcc
	v_cmp_lt_u32_e32 vcc, s33, v148
	v_add_u32_e32 v148, 0x73, v197
	s_nop 0
	v_cndmask_b32_e32 v69, v220, v69, vcc
	v_cmp_lt_u32_e32 vcc, s33, v148
	v_add_u32_e32 v148, 0x53, v197
	s_nop 0
	v_cndmask_b32_e32 v86, v220, v86, vcc
	v_cmp_lt_u32_e32 vcc, s33, v148
	v_add_u32_e32 v148, 0x72, v197
	s_nop 0
	v_cndmask_b32_e32 v70, v220, v70, vcc
	v_cmp_lt_u32_e32 vcc, s33, v148
	v_add_u32_e32 v148, 0x52, v197
	s_nop 0
	v_cndmask_b32_e32 v87, v220, v87, vcc
	v_cmp_lt_u32_e32 vcc, s33, v148
	v_add_u32_e32 v148, 0x71, v197
	s_nop 0
	v_cndmask_b32_e32 v71, v220, v71, vcc
	v_cmp_lt_u32_e32 vcc, s33, v148
	v_add_u32_e32 v148, 0x51, v197
	s_nop 0
	v_cndmask_b32_e32 v88, v220, v88, vcc
	v_cmp_lt_u32_e32 vcc, s33, v148
	v_add_u32_e32 v148, 0x70, v197
	s_nop 0
	v_cndmask_b32_e32 v72, v220, v72, vcc
	v_cmp_lt_u32_e32 vcc, s33, v148
	v_add_u32_e32 v148, 0x50, v197
	s_nop 0
	v_cndmask_b32_e32 v89, v220, v89, vcc
	v_cmp_lt_u32_e32 vcc, s33, v148
	v_add_u32_e32 v148, 0x6b, v197
	s_nop 0
	v_cndmask_b32_e32 v73, v220, v73, vcc
	v_cmp_lt_u32_e32 vcc, s33, v148
	v_add_u32_e32 v148, 0x4b, v197
	s_nop 0
	v_cndmask_b32_e32 v90, v220, v90, vcc
	v_cmp_lt_u32_e32 vcc, s33, v148
	v_add_u32_e32 v148, 0x6a, v197
	s_nop 0
	v_cndmask_b32_e32 v74, v220, v74, vcc
	v_cmp_lt_u32_e32 vcc, s33, v148
	v_add_u32_e32 v148, 0x4a, v197
	s_nop 0
	v_cndmask_b32_e32 v91, v220, v91, vcc
	v_cmp_lt_u32_e32 vcc, s33, v148
	v_add_u32_e32 v148, 0x69, v197
	s_nop 0
	v_cndmask_b32_e32 v75, v220, v75, vcc
	v_cmp_lt_u32_e32 vcc, s33, v148
	v_add_u32_e32 v148, 0x49, v197
	s_nop 0
	v_cndmask_b32_e32 v92, v220, v92, vcc
	v_cmp_lt_u32_e32 vcc, s33, v148
	v_add_u32_e32 v148, 0x68, v197
	s_nop 0
	v_cndmask_b32_e32 v76, v220, v76, vcc
	v_cmp_lt_u32_e32 vcc, s33, v148
	v_add_u32_e32 v148, 0x48, v197
	s_nop 0
	v_cndmask_b32_e32 v93, v220, v93, vcc
	v_cmp_lt_u32_e32 vcc, s33, v148
	v_add_u32_e32 v148, 0x63, v197
	s_nop 0
	v_cndmask_b32_e32 v77, v220, v77, vcc
	v_cmp_lt_u32_e32 vcc, s33, v148
	v_add_u32_e32 v148, 0x43, v197
	s_nop 0
	v_cndmask_b32_e32 v94, v220, v94, vcc
	v_cmp_lt_u32_e32 vcc, s33, v148
	v_add_u32_e32 v148, 0x62, v197
	s_nop 0
	v_cndmask_b32_e32 v78, v220, v78, vcc
	v_cmp_lt_u32_e32 vcc, s33, v148
	v_add_u32_e32 v148, 0x42, v197
	s_nop 0
	v_cndmask_b32_e32 v95, v220, v95, vcc
	v_cmp_lt_u32_e32 vcc, s33, v148
	v_add_u32_e32 v148, 0x61, v197
	s_nop 0
	v_cndmask_b32_e32 v79, v220, v79, vcc
	v_cmp_lt_u32_e32 vcc, s33, v148
	v_add_u32_e32 v148, 0x41, v197
	s_nop 0
	v_cndmask_b32_e32 v96, v220, v96, vcc
	v_cmp_lt_u32_e32 vcc, s33, v148
	v_add_u32_e32 v148, 0x60, v197
	s_nop 0
	v_cndmask_b32_e32 v80, v220, v80, vcc
	v_cmp_lt_u32_e32 vcc, s33, v148
	v_add_u32_e32 v148, 64, v197
	s_nop 0
	v_cndmask_b32_e32 v97, v220, v97, vcc
	v_cmp_lt_u32_e32 vcc, s33, v148
	s_nop 1
	v_cndmask_b32_e32 v81, v220, v81, vcc

; __device__ __forceinline__ void partialSM(f32x16& p0, f32x16& p1, float& m_reg, float& mn, float& alpha, bool rs) {
;     ...
;     if (__builtin_expect(__all((pmax - m_reg) * SCALE <= THR), 1)) { mn = m_reg; alpha = 1.f; }
;     else { mn = fmaxf(m_reg, pmax); alpha = __builtin_amdgcn_exp2f((m_reg - mn) * C2); m_reg = mn; }
;     const float mnL = rs ? -mn * C2 : -__builtin_inff();
;     for (int r = 0; r < 16; ++r) p0[r] = fmaf(p0[r], C2, mnL); for (int r = 0; r < 16; ++r) p1[r] = fmaf(p1[r], C2, mnL);
;     for (int r = 0; r < 16; ++r) p0[r] = __builtin_amdgcn_exp2f(p0[r]);
; }
.LBB0_95:
	v_cndmask_b32_e64 v179, v148, v198, s[42:43]
	v_mul_f32_e32 v148, 0xbe0293ee, v179
	v_cndmask_b32_e64 v180, v220, v148, s[40:41]
	v_fmamk_f32 v82, v82, 0x3e0293ee, v180
	v_fmamk_f32 v83, v83, 0x3e0293ee, v180
	v_fmamk_f32 v84, v84, 0x3e0293ee, v180
	v_fmamk_f32 v85, v85, 0x3e0293ee, v180
	v_fmamk_f32 v86, v86, 0x3e0293ee, v180
	v_fmamk_f32 v87, v87, 0x3e0293ee, v180
	v_fmamk_f32 v88, v88, 0x3e0293ee, v180
	v_fmamk_f32 v89, v89, 0x3e0293ee, v180
	v_fmamk_f32 v90, v90, 0x3e0293ee, v180
	v_fmamk_f32 v91, v91, 0x3e0293ee, v180
	v_fmamk_f32 v92, v92, 0x3e0293ee, v180
	v_fmamk_f32 v93, v93, 0x3e0293ee, v180
	v_fmamk_f32 v94, v94, 0x3e0293ee, v180
	v_fmamk_f32 v95, v95, 0x3e0293ee, v180
	v_fmamk_f32 v96, v96, 0x3e0293ee, v180
	v_fmamk_f32 v97, v97, 0x3e0293ee, v180
	v_exp_f32_e32 v148, v82
	v_exp_f32_e32 v163, v83
	v_exp_f32_e32 v149, v84
	v_exp_f32_e32 v162, v85
	v_exp_f32_e32 v150, v86
	v_exp_f32_e32 v161, v87
	v_exp_f32_e32 v151, v88
	v_exp_f32_e32 v160, v89
	v_exp_f32_e32 v152, v90
	v_exp_f32_e32 v159, v91
	v_exp_f32_e32 v153, v92
	v_exp_f32_e32 v158, v93
	v_exp_f32_e32 v154, v94
	v_exp_f32_e32 v157, v95
	v_exp_f32_e32 v155, v96
	v_exp_f32_e32 v156, v97
	v_fmamk_f32 v203, v73, 0x3e0293ee, v180
	v_fmamk_f32 v204, v74, 0x3e0293ee, v180
	v_fmamk_f32 v208, v66, 0x3e0293ee, v180
	v_fmamk_f32 v209, v67, 0x3e0293ee, v180
	v_fmamk_f32 v223, v68, 0x3e0293ee, v180
	v_fmamk_f32 v224, v69, 0x3e0293ee, v180
	v_fmamk_f32 v225, v70, 0x3e0293ee, v180
	v_fmamk_f32 v198, v71, 0x3e0293ee, v180
	v_fmamk_f32 v201, v72, 0x3e0293ee, v180
	v_fmamk_f32 v205, v75, 0x3e0293ee, v180
	v_fmamk_f32 v206, v76, 0x3e0293ee, v180
	v_fmamk_f32 v207, v77, 0x3e0293ee, v180
	v_fmamk_f32 v181, v78, 0x3e0293ee, v180
	v_fmamk_f32 v226, v79, 0x3e0293ee, v180
	v_fmamk_f32 v227, v80, 0x3e0293ee, v180
	v_fmac_f32_e32 v180, 0x3e0293ee, v81
	s_waitcnt lgkmcnt(0)
	s_barrier
; __device__ __forceinline__ void finishSM(f32x16& p0, f32x16& p1, float alpha, float& l_reg, bf16x8& pa0, bf16x8& pa1, bf16x8& pa2, bf16x8& pa3) {
;     for (int r = 0; r < 16; ++r) p1[r] = __builtin_amdgcn_exp2f(p1[r]);
;     float ps = 0; for (int r = 0; r < 16; ++r) ps += p0[r]; for (int r = 0; r < 16; ++r) ps += p1[r];
;     { auto rr = __builtin_amdgcn_permlane32_swap(__float_as_uint(ps), __float_as_uint(ps), false, false);
;       ps = __uint_as_float(rr[0]) + __uint_as_float(rr[1]); }
;     l_reg = l_reg * alpha + ps;
;     ...
;     PK4(p0, 0, pa0); PK4(p0, 8, pa1); PK4(p1, 0, pa2); PK4(p1, 8, pa3);
;     ...
; }
; template <int KB>
; __device__ __forceinline__ void qkt(f32x16& p0, f32x16& p1, const char* K_lds, int r32, int hi, const bf16x8* qr) {
;     p0 = f32x16{}; p1 = f32x16{};
;     const char* kb[4];
; #pragma unroll
;     for (int dd = 0; dd < 4; ++dd) kb[dd] = K_lds + KB * SHM_K + KSWZ(r32, (dd * 16 + hi * 8) * 2);
; #pragma unroll
;     for (int d0 = 0; d0 < 8; ++d0) { const char* a = kb[d0 & 3] + (d0 >> 2) * 128;
;         bf16x8 b0 = *reinterpret_cast<const bf16x8*>(a);
;         bf16x8 b1 = *reinterpret_cast<const bf16x8*>(a + 32 * 256);
;         p0 = __builtin_amdgcn_mfma_f32_32x32x16_bf16(b0, qr[d0], p0, 0, 0, 0);
;         p1 = __builtin_amdgcn_mfma_f32_32x32x16_bf16(b1, qr[d0], p1, 0, 0, 0); }
; }
	ds_read_b128 v[66:69], v169 offset:32768
	ds_read_b128 v[70:73], v169 offset:40960
	ds_read_b128 v[172:175], v193 offset:32768
	ds_read_b128 v[228:231], v193 offset:40960
	s_lshl_b32 m0, s32, 1
	s_sub_i32 m0, m0, 0x10000
	s_nop 0
	global_load_lds_dwordx4 v[100:101], off
	s_add_i32 m0, m0, 896
	s_nop 0
	global_load_lds_dwordx4 v[100:101], off offset:128
	v_exp_f32_e32 v198, v198
	v_exp_f32_e32 v201, v201
	v_exp_f32_e32 v214, v204
	v_exp_f32_e32 v205, v205
	v_exp_f32_e32 v206, v206
	v_exp_f32_e32 v207, v207
	v_exp_f32_e32 v181, v181
	v_exp_f32_e32 v215, v226
	v_exp_f32_e32 v216, v227
	v_exp_f32_e32 v180, v180
	v_exp_f32_e32 v218, v209
	v_exp_f32_e32 v209, v203
	v_add_f32_e32 v203, 0, v148
	v_add_f32_e32 v203, v163, v203
	v_add_f32_e32 v203, v149, v203
	v_add_f32_e32 v203, v162, v203
	v_add_f32_e32 v203, v150, v203
	v_add_f32_e32 v203, v161, v203
	v_add_f32_e32 v203, v151, v203
	v_add_f32_e32 v203, v160, v203
	s_waitcnt lgkmcnt(3)
	v_mfma_f32_32x32x16_bf16 v[82:97], v[66:69], v[132:135], 0
	v_add_f32_e32 v203, v152, v203
	v_add_f32_e32 v203, v159, v203
	v_add_f32_e32 v203, v153, v203
	v_add_f32_e32 v203, v158, v203
	s_waitcnt lgkmcnt(2)
	v_mfma_f32_32x32x16_bf16 v[66:81], v[70:73], v[132:135], 0
	v_exp_f32_e32 v217, v208
	v_add_f32_e32 v203, v154, v203
	v_add_f32_e32 v203, v157, v203
	v_exp_f32_e32 v219, v223
	s_waitcnt lgkmcnt(1)
	v_mfma_f32_32x32x16_bf16 v[82:97], v[172:175], v[128:131], v[82:97]
	v_add_f32_e32 v203, v155, v203
	v_exp_f32_e32 v222, v224
	v_add_f32_e32 v203, v156, v203
	v_exp_f32_e32 v208, v225
	s_waitcnt lgkmcnt(0)
	v_mfma_f32_32x32x16_bf16 v[66:81], v[228:231], v[128:131], v[66:81]
	v_add_f32_e32 v203, v217, v203
	v_add_f32_e32 v203, v218, v203
	v_add_f32_e32 v203, v219, v203
	v_add_f32_e32 v203, v222, v203
	ds_read_b128 v[172:175], v194 offset:32768
	ds_read_b128 v[228:231], v194 offset:40960
	s_waitcnt lgkmcnt(1)
	v_mfma_f32_32x32x16_bf16 v[82:97], v[172:175], v[124:127], v[82:97]
	v_add_f32_e32 v203, v208, v203
	v_add_f32_e32 v203, v198, v203
	v_add_f32_e32 v203, v201, v203
	v_add_f32_e32 v203, v209, v203
	s_waitcnt lgkmcnt(0)
	v_mfma_f32_32x32x16_bf16 v[66:81], v[228:231], v[124:127], v[66:81]
	v_add_f32_e32 v203, v214, v203
	v_add_f32_e32 v203, v205, v203
	v_add_f32_e32 v203, v206, v203
	v_add_f32_e32 v203, v207, v203
	ds_read_b128 v[172:175], v195 offset:32768
	ds_read_b128 v[228:231], v195 offset:40960
	s_waitcnt lgkmcnt(1)
	v_mfma_f32_32x32x16_bf16 v[82:97], v[172:175], v[120:123], v[82:97]
	v_add_f32_e32 v203, v181, v203
	v_add_f32_e32 v203, v215, v203
	v_add_f32_e32 v203, v216, v203
	v_add_f32_e32 v203, v180, v203
	s_waitcnt lgkmcnt(0)
	v_mfma_f32_32x32x16_bf16 v[66:81], v[228:231], v[120:123], v[66:81]
	v_mov_b32_e32 v204, v203
	v_cvt_pk_bf16_f32 v148, v148, v163
	v_cvt_pk_bf16_f32 v149, v149, v162
	v_cvt_pk_bf16_f32 v150, v150, v161
	ds_read_b128 v[172:175], v169 offset:32896
	ds_read_b128 v[228:231], v169 offset:41088
	s_waitcnt lgkmcnt(1)
	v_mfma_f32_32x32x16_bf16 v[82:97], v[172:175], v[116:119], v[82:97]
	v_cvt_pk_bf16_f32 v151, v151, v160
	v_cvt_pk_bf16_f32 v152, v152, v159
	v_cvt_pk_bf16_f32 v153, v153, v158
	v_cvt_pk_bf16_f32 v154, v154, v157
	s_waitcnt lgkmcnt(0)
	v_mfma_f32_32x32x16_bf16 v[66:81], v[228:231], v[116:119], v[66:81]
	v_cvt_pk_bf16_f32 v155, v155, v156
	v_cvt_pk_bf16_f32 v156, v217, v218
	v_cvt_pk_bf16_f32 v157, v219, v222
	ds_read_b128 v[172:175], v193 offset:32896
	ds_read_b128 v[228:231], v193 offset:41088
	s_waitcnt lgkmcnt(1)
	v_mfma_f32_32x32x16_bf16 v[82:97], v[172:175], v[112:115], v[82:97]
	v_cvt_pk_bf16_f32 v158, v208, v198
	v_cvt_pk_bf16_f32 v159, v201, v209
	v_cvt_pk_bf16_f32 v160, v214, v205
	s_waitcnt lgkmcnt(0)
	v_mfma_f32_32x32x16_bf16 v[66:81], v[228:231], v[112:115], v[66:81]
	v_cvt_pk_bf16_f32 v161, v206, v207
	v_cvt_pk_bf16_f32 v162, v181, v215
	v_cvt_pk_bf16_f32 v163, v216, v180
	ds_read_b128 v[172:175], v194 offset:32896
	ds_read_b128 v[228:231], v194 offset:41088
	s_waitcnt lgkmcnt(1)
	v_mfma_f32_32x32x16_bf16 v[82:97], v[172:175], v[108:111], v[82:97]
	s_nop 1
	v_permlane32_swap_b32_e32 v203, v204
	v_permlane32_swap_b32_e32 v148, v150
	v_permlane32_swap_b32_e32 v149, v151
	s_waitcnt lgkmcnt(0)
	v_mfma_f32_32x32x16_bf16 v[66:81], v[228:231], v[108:111], v[66:81]
	v_permlane32_swap_b32_e32 v152, v154
	v_permlane32_swap_b32_e32 v153, v155
	v_permlane32_swap_b32_e32 v156, v158
	ds_read_b128 v[172:175], v195 offset:32896
	ds_read_b128 v[228:231], v195 offset:41088
	ds_read_b64_tr_b16 v[206:207], v185 offset:0x5000
	ds_read_b64_tr_b16 v[208:209], v185 offset:0x5800
	ds_read_b64_tr_b16 v[224:225], v185 offset:0x6000
	ds_read_b64_tr_b16 v[226:227], v185 offset:0x6800
	s_waitcnt lgkmcnt(5)
	v_mfma_f32_32x32x16_bf16 v[82:97], v[172:175], v[104:107], v[82:97]
	v_permlane32_swap_b32_e32 v157, v159
	v_permlane32_swap_b32_e32 v160, v162
	v_permlane32_swap_b32_e32 v161, v163
	s_waitcnt lgkmcnt(4)
	v_mfma_f32_32x32x16_bf16 v[66:81], v[228:231], v[104:107], v[66:81]
	ds_read_b64_tr_b16 v[172:173], v185 offset:0x4000
	ds_read_b64_tr_b16 v[174:175], v185 offset:0x4800
	ds_read_b64_tr_b16 v[228:229], v185 offset:0x7000
	ds_read_b64_tr_b16 v[230:231], v185 offset:0x7800
	s_cmp_lt_u32 s3, s2
	s_cselect_b64 s[22:23], -1, 0
	s_cmp_ge_u32 s3, s2
	s_cbranch_scc1 .LBB0_97
	v_add_u32_e32 v242, 0x41, v178
	v_add_u32_e32 v246, 0x61, v178
	v_ashrrev_i32_e32 v243, 31, v242
	v_ashrrev_i32_e32 v247, 31, v246
	v_lshlrev_b64 v[140:141], 8, v[242:243]
	v_lshlrev_b64 v[142:143], 8, v[246:247]
	v_lshl_add_u64 v[242:243], v[238:239], 0, v[140:141]
	v_lshl_add_u64 v[140:141], v[234:235], 0, v[140:141]
	v_lshl_add_u64 v[144:145], v[234:235], 0, v[142:143]
	s_nop 0
	s_nop 0
	s_add_i32 m0, s32, 0x4000
	s_nop 0
	global_load_lds_dwordx4 v[140:141], off
	s_nop 0
	s_add_i32 m0, s32, 0x6000
	s_nop 0
	global_load_lds_dwordx4 v[144:145], off
	s_mov_b32 s100, 1
